# v27: v17 + relaxed first-trip counted waits after the SwiGLU epilogue in FFN-up (vmcnt 8->16, 6->14 while the epilogue stores drain)
# speedup vs baseline: 1.0028x; 1.0028x over previous
.LBB0_848:
	s_and_b32 s16, s0, 3
	s_add_i32 m0, s21, 0x18000
	v_lshl_add_u64 v[10:11], v[10:11], 0, s[48:49]
	s_lshl_b32 s41, s1, 6
	s_lshl_b32 s1, s1, 13
	s_lshl_b32 s11, s16, 12
	s_waitcnt vmcnt(2)
	s_barrier
	global_load_lds_dwordx4 v[10:11], off
	v_lshl_add_u64 v[8:9], v[8:9], 0, s[48:49]
	s_add_i32 m0, s21, 0x1a000
	s_add_i32 s42, s21, 0x8000
	s_add_i32 s43, s21, 0xa000
	global_load_lds_dwordx4 v[8:9], off
	v_lshl_add_u64 v[4:5], v[4:5], 0, s[48:49]
	s_mov_b32 m0, s42
	s_add_u32 s14, s26, 0x80080
	global_load_lds_dwordx4 v[4:5], off
	v_lshl_add_u64 v[4:5], v[6:7], 0, s[48:49]
	s_mov_b32 m0, s43
	s_addc_u32 s15, s27, 0
	global_load_lds_dwordx4 v[4:5], off
	s_add_i32 m0, s21, 0x1c000
	v_lshl_add_u64 v[4:5], s[14:15], 0, v[152:153]
	global_load_lds_dwordx4 v[4:5], off
	v_lshl_add_u64 v[4:5], s[14:15], 0, v[156:157]
	s_add_i32 m0, s21, 0x1e000
	s_lshl_b32 s14, s0, 5
	global_load_lds_dwordx4 v[4:5], off
	v_lshrrev_b32_e32 v4, 1, v12
	v_and_b32_e32 v149, 24, v4
	s_ashr_i32 s15, s14, 31
	v_and_b32_e32 v147, 15, v12
	v_lshlrev_b32_e32 v4, 1, v149
	s_lshl_b64 s[14:15], s[14:15], 5
	v_lshl_or_b32 v5, v147, 6, v4
	v_and_b32_e32 v6, 32, v148
	s_cmpk_lt_u32 s10, 0x100
	v_bitop3_b32 v7, v5, s1, v6 bitop3:0xde
	v_bitop3_b32 v166, v5, s11, v6 bitop3:0xde
	s_cselect_b64 s[10:11], -1, 0
	s_bfe_u32 s50, s0, 0x10001
	s_ashr_i32 s1, s41, 31
	s_lshl_b32 s51, s16, 7
	s_ashr_i32 s52, s28, 31
	v_or_b32_e32 v8, s41, v147
	v_mov_b32_e32 v9, s1
	s_add_u32 s12, s12, s14
	v_lshlrev_b64 v[8:9], 7, v[8:9]
	s_addc_u32 s13, s13, s15
	s_lshl_b32 s0, s0, 6
	v_lshl_add_u64 v[8:9], s[8:9], 0, v[8:9]
	s_and_b32 s44, s0, 64
	v_readlane_b32 s1, v254, 14
	v_lshl_add_u64 v[8:9], v[8:9], 0, s[44:45]
	v_mov_b32_e32 v5, v211
	v_lshl_add_u32 v10, v146, 5, s1
	v_lshl_add_u64 v[4:5], v[8:9], 0, v[4:5]
	s_mov_b64 s[0:1], 0x33000000
	v_lshl_add_u64 v[160:161], v[4:5], 0, s[0:1]
	v_lshlrev_b32_e32 v4, 15, v3
	v_and_b32_e32 v4, 0xffff0000, v4
	v_lshl_add_u32 v4, v13, 12, v4
	v_and_b32_e32 v3, 1, v3
	v_lshl_or_b32 v3, v3, 6, v4
	v_lshl_add_u32 v162, v14, 1, v3
	v_lshlrev_b32_e32 v3, 15, v15
	v_and_b32_e32 v3, 0xffff0000, v3
	s_waitcnt vmcnt(6)
	v_and_b32_e32 v6, 0xfc, v148
	v_lshl_add_u32 v3, v16, 12, v3
	v_and_b32_e32 v4, 1, v15
	v_lshlrev_b32_e32 v210, 2, v6
	v_lshl_or_b32 v3, v4, 6, v3
	v_lshl_add_u32 v167, v12, 4, s63
	v_lshl_add_u64 v[158:159], s[12:13], 0, v[210:211]
	v_mov_b32_e32 v163, v211
	v_lshl_add_u32 v164, v17, 1, v3
	v_mov_b32_e32 v165, v211
	s_mov_b32 s53, 0
	v_lshlrev_b32_e32 v210, 2, v6
	v_add_u32_e32 v168, 0, v7
	v_add_u32_e32 v169, v10, v2
	s_barrier
	s_mov_b32 s98, 0
	s_branch .LBB0_851

.LBB0_854:
	s_add_u32 s67, s24, 0xfff80080
	s_addc_u32 s68, s25, -1
	s_and_b64 s[0:1], s[26:27], exec
	s_cselect_b32 s1, s57, s68
	s_cselect_b32 s0, s58, s67
	s_add_i32 s67, 0, 0x10000
	s_and_b64 s[26:27], s[26:27], exec
	s_cselect_b32 s27, s13, s61
	s_cselect_b32 s26, s59, s15
	s_add_i32 s72, 0, 0x14000
	v_add_u32_e32 v170, s67, v166
	v_add_u32_e32 v186, s72, v166
	ds_read_b128 v[134:137], v170
	ds_read_b128 v[138:141], v170 offset:1024
	ds_read_b128 v[142:145], v170 offset:2048
	ds_read_b128 v[170:173], v170 offset:3072
	ds_read_b128 v[174:177], v186
	ds_read_b128 v[178:181], v186 offset:1024
	ds_read_b128 v[182:185], v186 offset:2048
	ds_read_b128 v[186:189], v186 offset:3072
	v_lshl_add_u64 v[224:225], s[24:25], 0, v[162:163]
	s_add_i32 m0, s21, 0xc000
	ds_read_b128 v[190:193], v168
	ds_read_b128 v[194:197], v168 offset:1024
	ds_read_b128 v[198:201], v168 offset:2048
	ds_read_b128 v[202:205], v168 offset:3072
	ds_read_b128 v[206:209], v168 offset:4096
	ds_read_b128 v[216:219], v168 offset:5120
	ds_read_b128 v[220:223], v168 offset:6144
	ds_read_b128 v[234:237], v168 offset:7168
	global_load_lds_dwordx4 v[224:225], off
	v_lshl_add_u64 v[224:225], s[24:25], 0, v[164:165]
	s_add_i32 m0, s21, 0xe000
	s_nop 0
	global_load_lds_dwordx4 v[224:225], off
	s_cmp_lg_u32 s98, 0
	s_cbranch_scc1 .Lrw1_ffu
	s_waitcnt vmcnt(8)
.Lrw1j_ffu:
	s_waitcnt lgkmcnt(0)
	s_barrier
	s_setprio 1
	s_waitcnt lgkmcnt(0)
	v_mfma_f32_16x16x32_bf16 v[126:129], v[134:137], v[190:193], v[126:129]
	v_mfma_f32_16x16x32_bf16 v[118:121], v[142:145], v[190:193], v[118:121]
	v_mfma_f32_16x16x32_bf16 v[110:113], v[134:137], v[198:201], v[110:113]
	v_mfma_f32_16x16x32_bf16 v[106:109], v[142:145], v[198:201], v[106:109]
	v_mfma_f32_16x16x32_bf16 v[94:97], v[134:137], v[206:209], v[94:97]
	v_mfma_f32_16x16x32_bf16 v[90:93], v[142:145], v[206:209], v[90:93]
	v_mfma_f32_16x16x32_bf16 v[78:81], v[134:137], v[220:223], v[78:81]
	v_mfma_f32_16x16x32_bf16 v[74:77], v[142:145], v[220:223], v[74:77]
	v_mfma_f32_16x16x32_bf16 v[126:129], v[138:141], v[194:197], v[126:129]
	v_mfma_f32_16x16x32_bf16 v[118:121], v[170:173], v[194:197], v[118:121]
	v_mfma_f32_16x16x32_bf16 v[110:113], v[138:141], v[202:205], v[110:113]
	v_mfma_f32_16x16x32_bf16 v[106:109], v[170:173], v[202:205], v[106:109]
	v_mfma_f32_16x16x32_bf16 v[94:97], v[138:141], v[216:219], v[94:97]
	v_mfma_f32_16x16x32_bf16 v[90:93], v[170:173], v[216:219], v[90:93]
	v_mfma_f32_16x16x32_bf16 v[78:81], v[138:141], v[234:237], v[78:81]
	v_mfma_f32_16x16x32_bf16 v[74:77], v[170:173], v[234:237], v[74:77]
	s_setprio 0
	s_setprio 1
	v_mfma_f32_16x16x32_bf16 v[122:125], v[174:177], v[190:193], v[122:125]
	v_mfma_f32_16x16x32_bf16 v[114:117], v[182:185], v[190:193], v[114:117]
	v_mfma_f32_16x16x32_bf16 v[102:105], v[174:177], v[198:201], v[102:105]
	v_mfma_f32_16x16x32_bf16 v[98:101], v[182:185], v[198:201], v[98:101]
	v_mfma_f32_16x16x32_bf16 v[86:89], v[174:177], v[206:209], v[86:89]
	v_mfma_f32_16x16x32_bf16 v[82:85], v[182:185], v[206:209], v[82:85]
	v_mfma_f32_16x16x32_bf16 v[70:73], v[174:177], v[220:223], v[70:73]
	v_mfma_f32_16x16x32_bf16 v[66:69], v[182:185], v[220:223], v[66:69]
	v_mfma_f32_16x16x32_bf16 v[122:125], v[178:181], v[194:197], v[122:125]
	v_mfma_f32_16x16x32_bf16 v[114:117], v[186:189], v[194:197], v[114:117]
	v_mfma_f32_16x16x32_bf16 v[102:105], v[178:181], v[202:205], v[102:105]
	v_mfma_f32_16x16x32_bf16 v[98:101], v[186:189], v[202:205], v[98:101]
	v_mfma_f32_16x16x32_bf16 v[86:89], v[178:181], v[216:219], v[86:89]
	v_mfma_f32_16x16x32_bf16 v[82:85], v[186:189], v[216:219], v[82:85]
	v_mfma_f32_16x16x32_bf16 v[70:73], v[178:181], v[234:237], v[70:73]
	v_mfma_f32_16x16x32_bf16 v[66:69], v[186:189], v[234:237], v[66:69]
	s_setprio 0
	s_barrier
	s_add_i32 s67, s67, s38
	v_lshl_add_u64 v[224:225], s[26:27], 0, v[152:153]
	s_mov_b32 m0, s67
	ds_read_b128 v[190:193], v168 offset:16384
	ds_read_b128 v[194:197], v168 offset:17408
	ds_read_b128 v[198:201], v168 offset:18432
	ds_read_b128 v[202:205], v168 offset:19456
	ds_read_b128 v[206:209], v168 offset:20480
	ds_read_b128 v[216:219], v168 offset:21504
	ds_read_b128 v[220:223], v168 offset:22528
	ds_read_b128 v[234:237], v168 offset:23552
	global_load_lds_dwordx4 v[224:225], off
	s_add_i32 m0, s67, 0x2000
	s_add_u32 s68, s26, 0x80000
	v_lshl_add_u64 v[238:239], s[26:27], 0, v[156:157]
	s_addc_u32 s69, s27, 0
	s_add_i32 s67, s72, s38
	global_load_lds_dwordx4 v[238:239], off
	v_lshl_add_u64 v[240:241], s[68:69], 0, v[152:153]
	s_mov_b32 m0, s67
	v_lshl_add_u64 v[242:243], s[0:1], 0, v[154:155]
	global_load_lds_dwordx4 v[240:241], off
	v_lshl_add_u64 v[240:241], s[68:69], 0, v[156:157]
	s_add_i32 m0, s67, 0x2000
	s_nop 0
	global_load_lds_dwordx4 v[240:241], off
	v_lshl_add_u64 v[240:241], s[0:1], 0, v[150:151]
	s_cmp_lg_u32 s98, 0
	s_cbranch_scc1 .Lrw2_ffu
	s_waitcnt vmcnt(6)
.Lrw2j_ffu:
	s_waitcnt lgkmcnt(0)
	s_barrier
	s_setprio 1
	s_waitcnt lgkmcnt(0)
	v_mfma_f32_16x16x32_bf16 v[62:65], v[134:137], v[190:193], v[62:65]
	v_mfma_f32_16x16x32_bf16 v[58:61], v[142:145], v[190:193], v[58:61]
	v_mfma_f32_16x16x32_bf16 v[46:49], v[134:137], v[198:201], v[46:49]
	v_mfma_f32_16x16x32_bf16 v[42:45], v[142:145], v[198:201], v[42:45]
	v_mfma_f32_16x16x32_bf16 v[30:33], v[134:137], v[206:209], v[30:33]
	v_mfma_f32_16x16x32_bf16 v[26:29], v[142:145], v[206:209], v[26:29]
	v_mfma_f32_16x16x32_bf16 v[14:17], v[134:137], v[220:223], v[14:17]
	v_mfma_f32_16x16x32_bf16 v[10:13], v[142:145], v[220:223], v[10:13]
	v_mfma_f32_16x16x32_bf16 v[62:65], v[138:141], v[194:197], v[62:65]
	v_mfma_f32_16x16x32_bf16 v[58:61], v[170:173], v[194:197], v[58:61]
	v_mfma_f32_16x16x32_bf16 v[46:49], v[138:141], v[202:205], v[46:49]
	v_mfma_f32_16x16x32_bf16 v[42:45], v[170:173], v[202:205], v[42:45]
	v_mfma_f32_16x16x32_bf16 v[30:33], v[138:141], v[216:219], v[30:33]
	v_mfma_f32_16x16x32_bf16 v[26:29], v[170:173], v[216:219], v[26:29]
	v_mfma_f32_16x16x32_bf16 v[14:17], v[138:141], v[234:237], v[14:17]
	v_mfma_f32_16x16x32_bf16 v[10:13], v[170:173], v[234:237], v[10:13]
	s_setprio 0
	s_setprio 1
	v_mfma_f32_16x16x32_bf16 v[54:57], v[174:177], v[190:193], v[54:57]
	v_mfma_f32_16x16x32_bf16 v[50:53], v[182:185], v[190:193], v[50:53]
	v_mfma_f32_16x16x32_bf16 v[38:41], v[174:177], v[198:201], v[38:41]
	v_mfma_f32_16x16x32_bf16 v[34:37], v[182:185], v[198:201], v[34:37]
	v_mfma_f32_16x16x32_bf16 v[22:25], v[174:177], v[206:209], v[22:25]
	v_mfma_f32_16x16x32_bf16 v[18:21], v[182:185], v[206:209], v[18:21]
	v_mfma_f32_16x16x32_bf16 v[6:9], v[174:177], v[220:223], v[6:9]
	v_mfma_f32_16x16x32_bf16 v[2:5], v[182:185], v[220:223], v[2:5]
	v_mfma_f32_16x16x32_bf16 v[54:57], v[178:181], v[194:197], v[54:57]
	v_mfma_f32_16x16x32_bf16 v[50:53], v[186:189], v[194:197], v[50:53]
	v_mfma_f32_16x16x32_bf16 v[38:41], v[178:181], v[202:205], v[38:41]
	v_mfma_f32_16x16x32_bf16 v[34:37], v[186:189], v[202:205], v[34:37]
	v_mfma_f32_16x16x32_bf16 v[22:25], v[178:181], v[216:219], v[22:25]
	v_mfma_f32_16x16x32_bf16 v[18:21], v[186:189], v[216:219], v[18:21]
	v_mfma_f32_16x16x32_bf16 v[6:9], v[178:181], v[234:237], v[6:9]
	v_mfma_f32_16x16x32_bf16 v[2:5], v[186:189], v[234:237], v[2:5]
	s_setprio 0
	s_barrier
	s_add_i32 s67, 0, 0x18000
	s_add_i32 s68, 0, 0x1c000
	v_add_u32_e32 v170, s67, v166
	v_add_u32_e32 v186, s68, v166
	ds_read_b128 v[134:137], v170
	ds_read_b128 v[138:141], v170 offset:1024
	ds_read_b128 v[142:145], v170 offset:2048
	ds_read_b128 v[170:173], v170 offset:3072
	ds_read_b128 v[174:177], v186
	ds_read_b128 v[178:181], v186 offset:1024
	ds_read_b128 v[182:185], v186 offset:2048
	ds_read_b128 v[186:189], v186 offset:3072
	s_add_u32 s0, s0, 0x80000
	s_addc_u32 s1, s1, 0
	s_mov_b32 m0, s39
	v_lshl_add_u64 v[244:245], s[0:1], 0, v[150:151]
	ds_read_b128 v[190:193], v168 offset:32768
	ds_read_b128 v[194:197], v168 offset:33792
	ds_read_b128 v[198:201], v168 offset:34816
	ds_read_b128 v[202:205], v168 offset:35840
	ds_read_b128 v[206:209], v168 offset:36864
	ds_read_b128 v[216:219], v168 offset:37888
	ds_read_b128 v[220:223], v168 offset:38912
	ds_read_b128 v[234:237], v168 offset:39936
	global_load_lds_dwordx4 v[244:245], off
	v_lshl_add_u64 v[244:245], s[0:1], 0, v[154:155]
	s_mov_b32 m0, s40
	s_nop 0
	global_load_lds_dwordx4 v[244:245], off
	s_mov_b32 m0, s21
	s_nop 0
	global_load_lds_dwordx4 v[240:241], off
	s_mov_b32 m0, s23
	s_nop 0
	global_load_lds_dwordx4 v[242:243], off
	s_waitcnt vmcnt(8)
	s_waitcnt lgkmcnt(0)
	s_barrier
	s_setprio 1
	s_waitcnt lgkmcnt(0)
	v_mfma_f32_16x16x32_bf16 v[126:129], v[134:137], v[190:193], v[126:129]
	v_mfma_f32_16x16x32_bf16 v[118:121], v[142:145], v[190:193], v[118:121]
	v_mfma_f32_16x16x32_bf16 v[110:113], v[134:137], v[198:201], v[110:113]
	v_mfma_f32_16x16x32_bf16 v[106:109], v[142:145], v[198:201], v[106:109]
	v_mfma_f32_16x16x32_bf16 v[94:97], v[134:137], v[206:209], v[94:97]
	v_mfma_f32_16x16x32_bf16 v[90:93], v[142:145], v[206:209], v[90:93]
	v_mfma_f32_16x16x32_bf16 v[78:81], v[134:137], v[220:223], v[78:81]
	v_mfma_f32_16x16x32_bf16 v[74:77], v[142:145], v[220:223], v[74:77]
	v_mfma_f32_16x16x32_bf16 v[126:129], v[138:141], v[194:197], v[126:129]
	v_mfma_f32_16x16x32_bf16 v[118:121], v[170:173], v[194:197], v[118:121]
	v_mfma_f32_16x16x32_bf16 v[110:113], v[138:141], v[202:205], v[110:113]
	v_mfma_f32_16x16x32_bf16 v[106:109], v[170:173], v[202:205], v[106:109]
	v_mfma_f32_16x16x32_bf16 v[94:97], v[138:141], v[216:219], v[94:97]
	v_mfma_f32_16x16x32_bf16 v[90:93], v[170:173], v[216:219], v[90:93]
	v_mfma_f32_16x16x32_bf16 v[78:81], v[138:141], v[234:237], v[78:81]
	v_mfma_f32_16x16x32_bf16 v[74:77], v[170:173], v[234:237], v[74:77]
	s_setprio 0
	s_setprio 1
	v_mfma_f32_16x16x32_bf16 v[122:125], v[174:177], v[190:193], v[122:125]
	v_mfma_f32_16x16x32_bf16 v[114:117], v[182:185], v[190:193], v[114:117]
	v_mfma_f32_16x16x32_bf16 v[102:105], v[174:177], v[198:201], v[102:105]
	v_mfma_f32_16x16x32_bf16 v[98:101], v[182:185], v[198:201], v[98:101]
	v_mfma_f32_16x16x32_bf16 v[86:89], v[174:177], v[206:209], v[86:89]
	v_mfma_f32_16x16x32_bf16 v[82:85], v[182:185], v[206:209], v[82:85]
	v_mfma_f32_16x16x32_bf16 v[70:73], v[174:177], v[220:223], v[70:73]
	v_mfma_f32_16x16x32_bf16 v[66:69], v[182:185], v[220:223], v[66:69]
	v_mfma_f32_16x16x32_bf16 v[122:125], v[178:181], v[194:197], v[122:125]
	v_mfma_f32_16x16x32_bf16 v[114:117], v[186:189], v[194:197], v[114:117]
	v_mfma_f32_16x16x32_bf16 v[102:105], v[178:181], v[202:205], v[102:105]
	v_mfma_f32_16x16x32_bf16 v[98:101], v[186:189], v[202:205], v[98:101]
	v_mfma_f32_16x16x32_bf16 v[86:89], v[178:181], v[216:219], v[86:89]
	v_mfma_f32_16x16x32_bf16 v[82:85], v[186:189], v[216:219], v[82:85]
	v_mfma_f32_16x16x32_bf16 v[70:73], v[178:181], v[234:237], v[70:73]
	v_mfma_f32_16x16x32_bf16 v[66:69], v[186:189], v[234:237], v[66:69]
	s_setprio 0
	s_barrier
	s_add_i32 s0, s67, s38
	v_lshl_add_u64 v[224:225], v[224:225], 0, s[48:49]
	s_mov_b32 m0, s0
	ds_read_b128 v[190:193], v168 offset:49152
	ds_read_b128 v[194:197], v168 offset:50176
	ds_read_b128 v[198:201], v168 offset:51200
	ds_read_b128 v[202:205], v168 offset:52224
	ds_read_b128 v[206:209], v168 offset:53248
	ds_read_b128 v[216:219], v168 offset:54272
	ds_read_b128 v[220:223], v168 offset:55296
	ds_read_b128 v[234:237], v168 offset:56320
	global_load_lds_dwordx4 v[224:225], off
	s_add_i32 m0, s0, 0x2000
	s_add_u32 s0, s26, 0x80080
	v_lshl_add_u64 v[224:225], v[238:239], 0, s[48:49]
	s_addc_u32 s1, s27, 0
	s_add_i32 s26, s68, s38
	global_load_lds_dwordx4 v[224:225], off
	v_lshl_add_u64 v[224:225], s[0:1], 0, v[152:153]
	s_mov_b32 m0, s26
	s_nop 0
	global_load_lds_dwordx4 v[224:225], off
	v_lshl_add_u64 v[224:225], s[0:1], 0, v[156:157]
	s_add_i32 m0, s26, 0x2000
	s_nop 0
	global_load_lds_dwordx4 v[224:225], off
	v_lshl_add_u64 v[224:225], v[240:241], 0, s[48:49]
	s_mov_b32 m0, s42
	s_nop 0
	global_load_lds_dwordx4 v[224:225], off
	v_lshl_add_u64 v[224:225], v[242:243], 0, s[48:49]
	s_mov_b32 m0, s43
	s_nop 0
	global_load_lds_dwordx4 v[224:225], off
	s_waitcnt vmcnt(6)
	s_waitcnt lgkmcnt(0)
	s_barrier
	s_setprio 1
	s_waitcnt lgkmcnt(0)
	v_mfma_f32_16x16x32_bf16 v[62:65], v[134:137], v[190:193], v[62:65]
	v_mfma_f32_16x16x32_bf16 v[58:61], v[142:145], v[190:193], v[58:61]
	v_mfma_f32_16x16x32_bf16 v[46:49], v[134:137], v[198:201], v[46:49]
	v_mfma_f32_16x16x32_bf16 v[42:45], v[142:145], v[198:201], v[42:45]
	v_mfma_f32_16x16x32_bf16 v[30:33], v[134:137], v[206:209], v[30:33]
	v_mfma_f32_16x16x32_bf16 v[26:29], v[142:145], v[206:209], v[26:29]
	v_mfma_f32_16x16x32_bf16 v[14:17], v[134:137], v[220:223], v[14:17]
	v_mfma_f32_16x16x32_bf16 v[10:13], v[142:145], v[220:223], v[10:13]
	v_mfma_f32_16x16x32_bf16 v[62:65], v[138:141], v[194:197], v[62:65]
	v_mfma_f32_16x16x32_bf16 v[58:61], v[170:173], v[194:197], v[58:61]
	v_mfma_f32_16x16x32_bf16 v[46:49], v[138:141], v[202:205], v[46:49]
	v_mfma_f32_16x16x32_bf16 v[42:45], v[170:173], v[202:205], v[42:45]
	v_mfma_f32_16x16x32_bf16 v[30:33], v[138:141], v[216:219], v[30:33]
	v_mfma_f32_16x16x32_bf16 v[26:29], v[170:173], v[216:219], v[26:29]
	v_mfma_f32_16x16x32_bf16 v[14:17], v[138:141], v[234:237], v[14:17]
	v_mfma_f32_16x16x32_bf16 v[10:13], v[170:173], v[234:237], v[10:13]
	s_setprio 0
	s_setprio 1
	v_mfma_f32_16x16x32_bf16 v[54:57], v[174:177], v[190:193], v[54:57]
	v_mfma_f32_16x16x32_bf16 v[50:53], v[182:185], v[190:193], v[50:53]
	v_mfma_f32_16x16x32_bf16 v[38:41], v[174:177], v[198:201], v[38:41]
	v_mfma_f32_16x16x32_bf16 v[34:37], v[182:185], v[198:201], v[34:37]
	v_mfma_f32_16x16x32_bf16 v[22:25], v[174:177], v[206:209], v[22:25]
	v_mfma_f32_16x16x32_bf16 v[18:21], v[182:185], v[206:209], v[18:21]
	v_mfma_f32_16x16x32_bf16 v[6:9], v[174:177], v[220:223], v[6:9]
	v_mfma_f32_16x16x32_bf16 v[2:5], v[182:185], v[220:223], v[2:5]
	v_mfma_f32_16x16x32_bf16 v[54:57], v[178:181], v[194:197], v[54:57]
	v_mfma_f32_16x16x32_bf16 v[50:53], v[186:189], v[194:197], v[50:53]
	v_mfma_f32_16x16x32_bf16 v[38:41], v[178:181], v[202:205], v[38:41]
	v_mfma_f32_16x16x32_bf16 v[34:37], v[186:189], v[202:205], v[34:37]
	v_mfma_f32_16x16x32_bf16 v[22:25], v[178:181], v[216:219], v[22:25]
	v_mfma_f32_16x16x32_bf16 v[18:21], v[186:189], v[216:219], v[18:21]
	v_mfma_f32_16x16x32_bf16 v[6:9], v[178:181], v[234:237], v[6:9]
	v_mfma_f32_16x16x32_bf16 v[2:5], v[186:189], v[234:237], v[2:5]
	s_setprio 0
	s_barrier
	s_add_i32 s65, s65, 2
	s_add_u32 s24, s24, 0x100
	s_addc_u32 s25, s25, 0
	s_add_u32 s15, s15, 0x100
	s_addc_u32 s61, s61, 0
	s_cmp_gt_u32 s65, 29
	s_cbranch_scc1 .LBB0_857

.Lrw1_ffu:
	s_waitcnt vmcnt(16)
	s_branch .Lrw1j_ffu
.Lrw2_ffu:
	s_waitcnt vmcnt(14)
	s_mov_b32 s98, 0
	s_branch .Lrw2j_ffu

.LBB0_859:
	s_lshl_b32 s0, s53, 11
	s_and_b32 s0, s0, 0x800
	s_add_i32 s0, s0, 0
	s_add_i32 s0, s0, 0x20000
	s_mul_i32 s1, s20, 0x58
	s_lshl_b32 s13, s22, 1
	s_add_i32 s1, s1, s13
	s_add_i32 s13, s0, s51
	v_lshl_add_u32 v130, v149, 2, s13
	s_lshl_b32 s13, s41, 2
	s_add_i32 s0, s0, s13
	v_lshl_add_u32 v170, v147, 2, s0
	ds_read_b128 v[142:145], v130 offset:1024
	ds_read_b32 v172, v170
	ds_read_b128 v[134:137], v130 offset:1040
	ds_read_b128 v[138:141], v130 offset:1536
	ds_read_b128 v[130:133], v130 offset:1552
	s_or_b32 s0, s1, s50
	s_ashr_i32 s1, s0, 31
	s_lshl_b64 s[0:1], s[0:1], 15
	s_waitcnt lgkmcnt(0)
	v_pk_fma_f32 v[126:127], v[126:127], v[172:173], v[142:143] op_sel_hi:[1,0,1]
	v_pk_fma_f32 v[122:123], v[122:123], v[172:173], v[138:139] op_sel_hi:[1,0,1]
	v_pk_fma_f32 v[120:121], v[120:121], v[172:173], v[136:137] op_sel_hi:[1,0,1]
	v_pk_fma_f32 v[128:129], v[128:129], v[172:173], v[144:145] op_sel_hi:[1,0,1]
	v_pk_mul_f32 v[176:177], v[126:127], s[88:89] op_sel_hi:[1,0]
	v_pk_fma_f32 v[124:125], v[124:125], v[172:173], v[140:141] op_sel_hi:[1,0,1]
	v_pk_mul_f32 v[122:123], v[126:127], v[122:123]
	v_pk_fma_f32 v[118:119], v[118:119], v[172:173], v[134:135] op_sel_hi:[1,0,1]
	v_pk_mul_f32 v[126:127], v[120:121], s[88:89] op_sel_hi:[1,0]
	v_pk_mul_f32 v[174:175], v[128:129], s[88:89] op_sel_hi:[1,0]
	v_pk_mul_f32 v[124:125], v[128:129], v[124:125]
	v_pk_mul_f32 v[128:129], v[118:119], s[88:89] op_sel_hi:[1,0]
	v_exp_f32_e32 v126, v126
	v_exp_f32_e32 v127, v127
	v_exp_f32_e32 v176, v176
	v_exp_f32_e32 v174, v174
	v_exp_f32_e32 v175, v175
	v_exp_f32_e32 v177, v177
	v_exp_f32_e32 v128, v128
	v_exp_f32_e32 v129, v129
	v_pk_add_f32 v[126:127], v[126:127], 1.0 op_sel_hi:[1,0]
	v_pk_add_f32 v[174:175], v[174:175], 1.0 op_sel_hi:[1,0]
	v_pk_add_f32 v[176:177], v[176:177], 1.0 op_sel_hi:[1,0]
	v_pk_add_f32 v[128:129], v[128:129], 1.0 op_sel_hi:[1,0]
	v_rcp_f32_e32 v126, v126
	v_rcp_f32_e32 v127, v127
	v_rcp_f32_e32 v176, v176
	v_rcp_f32_e32 v174, v174
	v_rcp_f32_e32 v175, v175
	v_rcp_f32_e32 v177, v177
	v_rcp_f32_e32 v128, v128
	v_rcp_f32_e32 v129, v129
	v_pk_fma_f32 v[116:117], v[116:117], v[172:173], v[132:133] op_sel_hi:[1,0,1]
	v_pk_fma_f32 v[114:115], v[114:115], v[172:173], v[130:131] op_sel_hi:[1,0,1]
	v_pk_mul_f32 v[116:117], v[120:121], v[116:117]
	v_pk_mul_f32 v[114:115], v[118:119], v[114:115]
	v_pk_mul_f32 v[120:121], v[116:117], v[126:127]
	v_pk_mul_f32 v[124:125], v[124:125], v[174:175]
	v_pk_mul_f32 v[122:123], v[122:123], v[176:177]
	v_pk_mul_f32 v[114:115], v[114:115], v[128:129]
	v_cvt_pk_bf16_f32 v116, v122, v123
	v_cvt_pk_bf16_f32 v117, v124, v125
	s_nop 0
	v_cvt_pk_bf16_f32 v118, v114, v115
	v_cvt_pk_bf16_f32 v119, v120, v121
	ds_read_b32 v120, v170 offset:64
	v_lshl_add_u64 v[114:115], v[160:161], 0, s[0:1]
	global_store_dwordx4 v[114:115], v[116:119], off
	s_movk_i32 s0, 0x1000
	s_waitcnt lgkmcnt(0)
	v_pk_fma_f32 v[112:113], v[112:113], v[120:121], v[144:145] op_sel_hi:[1,0,1]
	v_pk_fma_f32 v[110:111], v[110:111], v[120:121], v[142:143] op_sel_hi:[1,0,1]
	v_pk_fma_f32 v[104:105], v[104:105], v[120:121], v[140:141] op_sel_hi:[1,0,1]
	v_pk_fma_f32 v[102:103], v[102:103], v[120:121], v[138:139] op_sel_hi:[1,0,1]
	v_pk_fma_f32 v[108:109], v[108:109], v[120:121], v[136:137] op_sel_hi:[1,0,1]
	v_pk_fma_f32 v[106:107], v[106:107], v[120:121], v[134:135] op_sel_hi:[1,0,1]
	v_pk_mul_f32 v[116:117], v[112:113], s[88:89] op_sel_hi:[1,0]
	v_pk_mul_f32 v[118:119], v[110:111], s[88:89] op_sel_hi:[1,0]
	v_pk_mul_f32 v[104:105], v[112:113], v[104:105]
	v_pk_mul_f32 v[102:103], v[110:111], v[102:103]
	v_pk_mul_f32 v[110:111], v[108:109], s[88:89] op_sel_hi:[1,0]
	v_pk_mul_f32 v[112:113], v[106:107], s[88:89] op_sel_hi:[1,0]
	v_exp_f32_e32 v118, v118
	v_exp_f32_e32 v119, v119
	v_exp_f32_e32 v112, v112
	v_exp_f32_e32 v110, v110
	v_exp_f32_e32 v111, v111
	v_exp_f32_e32 v113, v113
	v_exp_f32_e32 v116, v116
	v_exp_f32_e32 v117, v117
	v_pk_add_f32 v[118:119], v[118:119], 1.0 op_sel_hi:[1,0]
	v_pk_add_f32 v[110:111], v[110:111], 1.0 op_sel_hi:[1,0]
	v_pk_add_f32 v[112:113], v[112:113], 1.0 op_sel_hi:[1,0]
	v_pk_add_f32 v[116:117], v[116:117], 1.0 op_sel_hi:[1,0]
	v_rcp_f32_e32 v118, v118
	v_rcp_f32_e32 v119, v119
	v_rcp_f32_e32 v112, v112
	v_rcp_f32_e32 v110, v110
	v_rcp_f32_e32 v111, v111
	v_rcp_f32_e32 v113, v113
	v_rcp_f32_e32 v116, v116
	v_rcp_f32_e32 v117, v117
	v_pk_fma_f32 v[100:101], v[100:101], v[120:121], v[132:133] op_sel_hi:[1,0,1]
	v_pk_fma_f32 v[98:99], v[98:99], v[120:121], v[130:131] op_sel_hi:[1,0,1]
	v_pk_mul_f32 v[100:101], v[108:109], v[100:101]
	v_pk_mul_f32 v[98:99], v[106:107], v[98:99]
	v_pk_mul_f32 v[102:103], v[102:103], v[118:119]
	v_pk_mul_f32 v[106:107], v[100:101], v[110:111]
	v_pk_mul_f32 v[100:101], v[98:99], v[112:113]
	v_pk_mul_f32 v[104:105], v[104:105], v[116:117]
	v_cvt_pk_bf16_f32 v98, v102, v103
	s_nop 0
	v_cvt_pk_bf16_f32 v99, v104, v105
	v_cvt_pk_bf16_f32 v100, v100, v101
	v_cvt_pk_bf16_f32 v101, v106, v107
	ds_read_b32 v102, v170 offset:128
	global_store_dwordx4 v[114:115], v[98:101], off offset:2048
	s_waitcnt lgkmcnt(0)
	v_pk_fma_f32 v[96:97], v[96:97], v[102:103], v[144:145] op_sel_hi:[1,0,1]
	v_pk_fma_f32 v[94:95], v[94:95], v[102:103], v[142:143] op_sel_hi:[1,0,1]
	v_pk_fma_f32 v[88:89], v[88:89], v[102:103], v[140:141] op_sel_hi:[1,0,1]
	v_pk_fma_f32 v[86:87], v[86:87], v[102:103], v[138:139] op_sel_hi:[1,0,1]
	v_pk_fma_f32 v[92:93], v[92:93], v[102:103], v[136:137] op_sel_hi:[1,0,1]
	v_pk_fma_f32 v[90:91], v[90:91], v[102:103], v[134:135] op_sel_hi:[1,0,1]
	v_pk_mul_f32 v[98:99], v[96:97], s[88:89] op_sel_hi:[1,0]
	v_pk_mul_f32 v[100:101], v[94:95], s[88:89] op_sel_hi:[1,0]
	v_pk_mul_f32 v[88:89], v[96:97], v[88:89]
	v_pk_mul_f32 v[86:87], v[94:95], v[86:87]
	v_pk_mul_f32 v[94:95], v[92:93], s[88:89] op_sel_hi:[1,0]
	v_pk_mul_f32 v[96:97], v[90:91], s[88:89] op_sel_hi:[1,0]
	v_exp_f32_e32 v100, v100
	v_exp_f32_e32 v101, v101
	v_exp_f32_e32 v96, v96
	v_exp_f32_e32 v94, v94
	v_exp_f32_e32 v95, v95
	v_exp_f32_e32 v97, v97
	v_exp_f32_e32 v98, v98
	v_exp_f32_e32 v99, v99
	v_pk_add_f32 v[100:101], v[100:101], 1.0 op_sel_hi:[1,0]
	v_pk_add_f32 v[94:95], v[94:95], 1.0 op_sel_hi:[1,0]
	v_pk_add_f32 v[96:97], v[96:97], 1.0 op_sel_hi:[1,0]
	v_pk_add_f32 v[98:99], v[98:99], 1.0 op_sel_hi:[1,0]
	v_rcp_f32_e32 v100, v100
	v_rcp_f32_e32 v101, v101
	v_rcp_f32_e32 v96, v96
	v_rcp_f32_e32 v94, v94
	v_rcp_f32_e32 v95, v95
	v_rcp_f32_e32 v97, v97
	v_rcp_f32_e32 v98, v98
	v_rcp_f32_e32 v99, v99
	v_pk_fma_f32 v[84:85], v[84:85], v[102:103], v[132:133] op_sel_hi:[1,0,1]
	v_pk_fma_f32 v[82:83], v[82:83], v[102:103], v[130:131] op_sel_hi:[1,0,1]
	v_pk_mul_f32 v[84:85], v[92:93], v[84:85]
	v_pk_mul_f32 v[82:83], v[90:91], v[82:83]
	v_pk_mul_f32 v[86:87], v[86:87], v[100:101]
	v_pk_mul_f32 v[90:91], v[84:85], v[94:95]
	v_pk_mul_f32 v[84:85], v[82:83], v[96:97]
	v_pk_mul_f32 v[88:89], v[88:89], v[98:99]
	v_cvt_pk_bf16_f32 v82, v86, v87
	s_nop 0
	v_cvt_pk_bf16_f32 v83, v88, v89
	v_cvt_pk_bf16_f32 v84, v84, v85
	v_cvt_pk_bf16_f32 v85, v90, v91
	ds_read_b32 v86, v170 offset:192
	v_add_co_u32_e32 v88, vcc, s0, v114
	s_movk_i32 s0, 0x5000
	s_nop 0
	v_addc_co_u32_e32 v89, vcc, 0, v115, vcc
	s_waitcnt lgkmcnt(0)
	v_pk_fma_f32 v[80:81], v[80:81], v[86:87], v[144:145] op_sel_hi:[1,0,1]
	v_pk_fma_f32 v[78:79], v[78:79], v[86:87], v[142:143] op_sel_hi:[1,0,1]
	v_pk_fma_f32 v[72:73], v[72:73], v[86:87], v[140:141] op_sel_hi:[1,0,1]
	v_pk_fma_f32 v[70:71], v[70:71], v[86:87], v[138:139] op_sel_hi:[1,0,1]
	v_pk_fma_f32 v[76:77], v[76:77], v[86:87], v[136:137] op_sel_hi:[1,0,1]
	v_pk_fma_f32 v[74:75], v[74:75], v[86:87], v[134:135] op_sel_hi:[1,0,1]
	global_store_dwordx4 v[88:89], v[82:85], off
	v_pk_mul_f32 v[72:73], v[80:81], v[72:73]
	v_pk_mul_f32 v[70:71], v[78:79], v[70:71]
	v_pk_mul_f32 v[82:83], v[80:81], s[88:89] op_sel_hi:[1,0]
	v_pk_mul_f32 v[84:85], v[78:79], s[88:89] op_sel_hi:[1,0]
	v_pk_mul_f32 v[78:79], v[76:77], s[88:89] op_sel_hi:[1,0]
	v_pk_mul_f32 v[80:81], v[74:75], s[88:89] op_sel_hi:[1,0]
	v_exp_f32_e32 v84, v84
	v_exp_f32_e32 v85, v85
	v_exp_f32_e32 v80, v80
	v_exp_f32_e32 v78, v78
	v_exp_f32_e32 v79, v79
	v_exp_f32_e32 v81, v81
	v_exp_f32_e32 v82, v82
	v_exp_f32_e32 v83, v83
	v_pk_add_f32 v[84:85], v[84:85], 1.0 op_sel_hi:[1,0]
	v_pk_add_f32 v[78:79], v[78:79], 1.0 op_sel_hi:[1,0]
	v_pk_add_f32 v[80:81], v[80:81], 1.0 op_sel_hi:[1,0]
	v_pk_add_f32 v[82:83], v[82:83], 1.0 op_sel_hi:[1,0]
	v_rcp_f32_e32 v84, v84
	v_rcp_f32_e32 v85, v85
	v_rcp_f32_e32 v80, v80
	v_rcp_f32_e32 v78, v78
	v_rcp_f32_e32 v79, v79
	v_rcp_f32_e32 v81, v81
	v_rcp_f32_e32 v82, v82
	v_rcp_f32_e32 v83, v83
	v_pk_fma_f32 v[68:69], v[68:69], v[86:87], v[132:133] op_sel_hi:[1,0,1]
	v_pk_fma_f32 v[66:67], v[66:67], v[86:87], v[130:131] op_sel_hi:[1,0,1]
	v_pk_mul_f32 v[68:69], v[76:77], v[68:69]
	v_pk_mul_f32 v[66:67], v[74:75], v[66:67]
	v_pk_mul_f32 v[70:71], v[70:71], v[84:85]
	v_pk_mul_f32 v[74:75], v[68:69], v[78:79]
	v_pk_mul_f32 v[68:69], v[66:67], v[80:81]
	v_pk_mul_f32 v[72:73], v[72:73], v[82:83]
	v_cvt_pk_bf16_f32 v66, v70, v71
	s_nop 0
	v_cvt_pk_bf16_f32 v67, v72, v73
	v_cvt_pk_bf16_f32 v68, v68, v69
	v_cvt_pk_bf16_f32 v69, v74, v75
	ds_read_b32 v70, v170 offset:512
	global_store_dwordx4 v[88:89], v[66:69], off offset:2048
	s_waitcnt lgkmcnt(0)
	v_pk_fma_f32 v[64:65], v[64:65], v[70:71], v[144:145] op_sel_hi:[1,0,1]
	v_pk_fma_f32 v[62:63], v[62:63], v[70:71], v[142:143] op_sel_hi:[1,0,1]
	v_pk_mul_f32 v[66:67], v[64:65], s[88:89] op_sel_hi:[1,0]
	v_pk_mul_f32 v[68:69], v[62:63], s[88:89] op_sel_hi:[1,0]
	v_pk_fma_f32 v[56:57], v[56:57], v[70:71], v[140:141] op_sel_hi:[1,0,1]
	v_pk_fma_f32 v[54:55], v[54:55], v[70:71], v[138:139] op_sel_hi:[1,0,1]
	v_pk_fma_f32 v[60:61], v[60:61], v[70:71], v[136:137] op_sel_hi:[1,0,1]
	v_pk_fma_f32 v[58:59], v[58:59], v[70:71], v[134:135] op_sel_hi:[1,0,1]
	v_exp_f32_e32 v68, v68
	v_exp_f32_e32 v66, v66
	v_exp_f32_e32 v67, v67
	v_exp_f32_e32 v69, v69
	v_pk_mul_f32 v[56:57], v[64:65], v[56:57]
	v_pk_mul_f32 v[54:55], v[62:63], v[54:55]
	v_pk_mul_f32 v[62:63], v[60:61], s[88:89] op_sel_hi:[1,0]
	v_pk_mul_f32 v[64:65], v[58:59], s[88:89] op_sel_hi:[1,0]
	v_exp_f32_e32 v62, v62
	v_exp_f32_e32 v64, v64
	v_exp_f32_e32 v63, v63
	v_exp_f32_e32 v65, v65
	v_pk_add_f32 v[66:67], v[66:67], 1.0 op_sel_hi:[1,0]
	v_pk_add_f32 v[68:69], v[68:69], 1.0 op_sel_hi:[1,0]
	v_rcp_f32_e32 v66, v66
	v_rcp_f32_e32 v68, v68
	v_rcp_f32_e32 v67, v67
	v_rcp_f32_e32 v69, v69
	v_pk_add_f32 v[62:63], v[62:63], 1.0 op_sel_hi:[1,0]
	v_pk_add_f32 v[64:65], v[64:65], 1.0 op_sel_hi:[1,0]
	v_rcp_f32_e32 v62, v62
	v_rcp_f32_e32 v64, v64
	v_rcp_f32_e32 v63, v63
	v_rcp_f32_e32 v65, v65
	v_pk_fma_f32 v[52:53], v[52:53], v[70:71], v[132:133] op_sel_hi:[1,0,1]
	v_pk_fma_f32 v[50:51], v[50:51], v[70:71], v[130:131] op_sel_hi:[1,0,1]
	v_pk_mul_f32 v[56:57], v[56:57], v[66:67]
	v_pk_mul_f32 v[54:55], v[54:55], v[68:69]
	v_pk_mul_f32 v[52:53], v[60:61], v[52:53]
	v_pk_mul_f32 v[50:51], v[58:59], v[50:51]
	v_pk_mul_f32 v[58:59], v[52:53], v[62:63]
	v_pk_mul_f32 v[50:51], v[50:51], v[64:65]
	v_cvt_pk_bf16_f32 v52, v54, v55
	v_cvt_pk_bf16_f32 v53, v56, v57
	s_nop 0
	v_cvt_pk_bf16_f32 v54, v50, v51
	v_cvt_pk_bf16_f32 v55, v58, v59
	ds_read_b32 v56, v170 offset:576
	v_add_co_u32_e32 v50, vcc, s0, v114
	s_movk_i32 s0, 0x4000
	s_nop 0
	v_addc_co_u32_e32 v51, vcc, 0, v115, vcc
	s_waitcnt lgkmcnt(0)
	v_pk_fma_f32 v[48:49], v[48:49], v[56:57], v[144:145] op_sel_hi:[1,0,1]
	v_pk_fma_f32 v[46:47], v[46:47], v[56:57], v[142:143] op_sel_hi:[1,0,1]
	v_pk_fma_f32 v[40:41], v[40:41], v[56:57], v[140:141] op_sel_hi:[1,0,1]
	v_pk_fma_f32 v[38:39], v[38:39], v[56:57], v[138:139] op_sel_hi:[1,0,1]
	v_pk_fma_f32 v[44:45], v[44:45], v[56:57], v[136:137] op_sel_hi:[1,0,1]
	v_pk_fma_f32 v[42:43], v[42:43], v[56:57], v[134:135] op_sel_hi:[1,0,1]
	global_store_dwordx4 v[50:51], v[52:55], off offset:-4096
	v_pk_mul_f32 v[40:41], v[48:49], v[40:41]
	v_pk_mul_f32 v[38:39], v[46:47], v[38:39]
	v_pk_mul_f32 v[52:53], v[48:49], s[88:89] op_sel_hi:[1,0]
	v_pk_mul_f32 v[54:55], v[46:47], s[88:89] op_sel_hi:[1,0]
	v_pk_mul_f32 v[46:47], v[44:45], s[88:89] op_sel_hi:[1,0]
	v_pk_mul_f32 v[48:49], v[42:43], s[88:89] op_sel_hi:[1,0]
	v_exp_f32_e32 v54, v54
	v_exp_f32_e32 v55, v55
	v_exp_f32_e32 v48, v48
	v_exp_f32_e32 v46, v46
	v_exp_f32_e32 v47, v47
	v_exp_f32_e32 v49, v49
	v_exp_f32_e32 v52, v52
	v_exp_f32_e32 v53, v53
	v_pk_add_f32 v[54:55], v[54:55], 1.0 op_sel_hi:[1,0]
	v_pk_add_f32 v[46:47], v[46:47], 1.0 op_sel_hi:[1,0]
	v_pk_add_f32 v[48:49], v[48:49], 1.0 op_sel_hi:[1,0]
	v_pk_add_f32 v[52:53], v[52:53], 1.0 op_sel_hi:[1,0]
	v_rcp_f32_e32 v54, v54
	v_rcp_f32_e32 v55, v55
	v_rcp_f32_e32 v48, v48
	v_rcp_f32_e32 v46, v46
	v_rcp_f32_e32 v47, v47
	v_rcp_f32_e32 v49, v49
	v_rcp_f32_e32 v52, v52
	v_rcp_f32_e32 v53, v53
	v_pk_fma_f32 v[36:37], v[36:37], v[56:57], v[132:133] op_sel_hi:[1,0,1]
	v_pk_fma_f32 v[34:35], v[34:35], v[56:57], v[130:131] op_sel_hi:[1,0,1]
	v_pk_mul_f32 v[36:37], v[44:45], v[36:37]
	v_pk_mul_f32 v[34:35], v[42:43], v[34:35]
	v_pk_mul_f32 v[38:39], v[38:39], v[54:55]
	v_pk_mul_f32 v[42:43], v[36:37], v[46:47]
	v_pk_mul_f32 v[36:37], v[34:35], v[48:49]
	v_pk_mul_f32 v[40:41], v[40:41], v[52:53]
	v_cvt_pk_bf16_f32 v34, v38, v39
	s_nop 0
	v_cvt_pk_bf16_f32 v35, v40, v41
	v_cvt_pk_bf16_f32 v36, v36, v37
	v_cvt_pk_bf16_f32 v37, v42, v43
	ds_read_b32 v38, v170 offset:640
	v_add_co_u32_e32 v40, vcc, s0, v114
	s_mov_b64 s[0:1], -1
	s_nop 0
	v_addc_co_u32_e32 v41, vcc, 0, v115, vcc
	s_waitcnt lgkmcnt(0)
	v_pk_fma_f32 v[32:33], v[32:33], v[38:39], v[144:145] op_sel_hi:[1,0,1]
	v_pk_fma_f32 v[30:31], v[30:31], v[38:39], v[142:143] op_sel_hi:[1,0,1]
	v_pk_fma_f32 v[24:25], v[24:25], v[38:39], v[140:141] op_sel_hi:[1,0,1]
	v_pk_fma_f32 v[22:23], v[22:23], v[38:39], v[138:139] op_sel_hi:[1,0,1]
	v_pk_fma_f32 v[28:29], v[28:29], v[38:39], v[136:137] op_sel_hi:[1,0,1]
	v_pk_fma_f32 v[26:27], v[26:27], v[38:39], v[134:135] op_sel_hi:[1,0,1]
	global_store_dwordx4 v[40:41], v[34:37], off offset:2048
	v_pk_mul_f32 v[24:25], v[32:33], v[24:25]
	v_pk_mul_f32 v[22:23], v[30:31], v[22:23]
	v_pk_mul_f32 v[34:35], v[32:33], s[88:89] op_sel_hi:[1,0]
	v_pk_mul_f32 v[36:37], v[30:31], s[88:89] op_sel_hi:[1,0]
	v_pk_mul_f32 v[30:31], v[28:29], s[88:89] op_sel_hi:[1,0]
	v_pk_mul_f32 v[32:33], v[26:27], s[88:89] op_sel_hi:[1,0]
	v_exp_f32_e32 v36, v36
	v_exp_f32_e32 v37, v37
	v_exp_f32_e32 v32, v32
	v_exp_f32_e32 v30, v30
	v_exp_f32_e32 v31, v31
	v_exp_f32_e32 v33, v33
	v_exp_f32_e32 v34, v34
	v_exp_f32_e32 v35, v35
	v_pk_add_f32 v[36:37], v[36:37], 1.0 op_sel_hi:[1,0]
	v_pk_add_f32 v[30:31], v[30:31], 1.0 op_sel_hi:[1,0]
	v_pk_add_f32 v[32:33], v[32:33], 1.0 op_sel_hi:[1,0]
	v_pk_add_f32 v[34:35], v[34:35], 1.0 op_sel_hi:[1,0]
	v_rcp_f32_e32 v36, v36
	v_rcp_f32_e32 v37, v37
	v_rcp_f32_e32 v32, v32
	v_rcp_f32_e32 v30, v30
	v_rcp_f32_e32 v31, v31
	v_rcp_f32_e32 v33, v33
	v_rcp_f32_e32 v34, v34
	v_rcp_f32_e32 v35, v35
	v_pk_fma_f32 v[20:21], v[20:21], v[38:39], v[132:133] op_sel_hi:[1,0,1]
	v_pk_fma_f32 v[18:19], v[18:19], v[38:39], v[130:131] op_sel_hi:[1,0,1]
	v_pk_mul_f32 v[20:21], v[28:29], v[20:21]
	v_pk_mul_f32 v[18:19], v[26:27], v[18:19]
	v_pk_mul_f32 v[22:23], v[22:23], v[36:37]
	v_pk_mul_f32 v[26:27], v[20:21], v[30:31]
	v_pk_mul_f32 v[20:21], v[18:19], v[32:33]
	v_pk_mul_f32 v[24:25], v[24:25], v[34:35]
	v_cvt_pk_bf16_f32 v18, v22, v23
	s_andn2_b64 vcc, exec, s[8:9]
	v_cvt_pk_bf16_f32 v19, v24, v25
	v_cvt_pk_bf16_f32 v20, v20, v21
	v_cvt_pk_bf16_f32 v21, v26, v27
	ds_read_b32 v22, v170 offset:704
	global_store_dwordx4 v[50:51], v[18:21], off
	s_waitcnt lgkmcnt(0)
	v_pk_fma_f32 v[16:17], v[16:17], v[22:23], v[144:145] op_sel_hi:[1,0,1]
	v_pk_fma_f32 v[14:15], v[14:15], v[22:23], v[142:143] op_sel_hi:[1,0,1]
	v_pk_fma_f32 v[8:9], v[8:9], v[22:23], v[140:141] op_sel_hi:[1,0,1]
	v_pk_fma_f32 v[6:7], v[6:7], v[22:23], v[138:139] op_sel_hi:[1,0,1]
	v_pk_fma_f32 v[12:13], v[12:13], v[22:23], v[136:137] op_sel_hi:[1,0,1]
	v_pk_fma_f32 v[10:11], v[10:11], v[22:23], v[134:135] op_sel_hi:[1,0,1]
	v_pk_mul_f32 v[18:19], v[16:17], s[88:89] op_sel_hi:[1,0]
	v_pk_mul_f32 v[20:21], v[14:15], s[88:89] op_sel_hi:[1,0]
	v_pk_mul_f32 v[8:9], v[16:17], v[8:9]
	v_pk_mul_f32 v[6:7], v[14:15], v[6:7]
	v_pk_mul_f32 v[14:15], v[12:13], s[88:89] op_sel_hi:[1,0]
	v_pk_mul_f32 v[16:17], v[10:11], s[88:89] op_sel_hi:[1,0]
	v_exp_f32_e32 v14, v14
	v_exp_f32_e32 v16, v16
	v_exp_f32_e32 v15, v15
	v_exp_f32_e32 v17, v17
	v_exp_f32_e32 v20, v20
	v_exp_f32_e32 v18, v18
	v_exp_f32_e32 v19, v19
	v_exp_f32_e32 v21, v21
	v_pk_add_f32 v[14:15], v[14:15], 1.0 op_sel_hi:[1,0]
	v_pk_add_f32 v[16:17], v[16:17], 1.0 op_sel_hi:[1,0]
	v_pk_add_f32 v[18:19], v[18:19], 1.0 op_sel_hi:[1,0]
	v_pk_add_f32 v[20:21], v[20:21], 1.0 op_sel_hi:[1,0]
	v_rcp_f32_e32 v16, v16
	v_rcp_f32_e32 v14, v14
	v_rcp_f32_e32 v15, v15
	v_rcp_f32_e32 v17, v17
	v_rcp_f32_e32 v20, v20
	v_rcp_f32_e32 v18, v18
	v_rcp_f32_e32 v19, v19
	v_rcp_f32_e32 v21, v21
	v_pk_fma_f32 v[4:5], v[4:5], v[22:23], v[132:133] op_sel_hi:[1,0,1]
	v_pk_fma_f32 v[2:3], v[2:3], v[22:23], v[130:131] op_sel_hi:[1,0,1]
	v_pk_mul_f32 v[4:5], v[12:13], v[4:5]
	v_pk_mul_f32 v[2:3], v[10:11], v[2:3]
	v_pk_mul_f32 v[10:11], v[4:5], v[14:15]
	v_pk_mul_f32 v[4:5], v[2:3], v[16:17]
	v_pk_mul_f32 v[8:9], v[8:9], v[18:19]
	v_pk_mul_f32 v[6:7], v[6:7], v[20:21]
	s_nop 0
	v_cvt_pk_bf16_f32 v2, v6, v7
	v_cvt_pk_bf16_f32 v3, v8, v9
	v_cvt_pk_bf16_f32 v4, v4, v5
	v_cvt_pk_bf16_f32 v5, v10, v11
	s_mov_b32 s98, 1
	global_store_dwordx4 v[50:51], v[2:5], off offset:2048
	s_cbranch_vccnz .LBB0_850
	ds_read_b128 v[2:5], v169
	s_lshl_b32 s0, s44, 11
	s_and_b32 s0, s0, 0x800
	s_add_i32 s13, s0, 0
	s_add_i32 s13, s13, 0x20000
	s_waitcnt lgkmcnt(0)
	v_add_f32_e32 v2, v2, v3
	v_add_f32_e32 v3, v4, v5
	v_add_f32_e32 v2, v2, v3
	s_nop 1
	v_mov_b32_dpp v3, v2 quad_perm:[1,0,3,2] row_mask:0xf bank_mask:0xf bound_ctrl:1
	s_and_saveexec_b64 s[0:1], s[4:5]
	s_cbranch_execz .LBB0_863
	v_add_f32_e32 v2, v2, v3
	v_fmamk_f32 v2, v2, 0x3a000000, v1
	s_mov_b32 s8, 0xf800000
	v_mul_f32_e32 v3, 0x4f800000, v2
	v_cmp_gt_f32_e32 vcc, s8, v2
	s_nop 1
	v_cndmask_b32_e32 v2, v2, v3, vcc
	v_sqrt_f32_e32 v3, v2
	s_nop 0
	v_add_u32_e32 v4, -1, v3
	v_fma_f32 v6, -v4, v3, v2
	v_add_u32_e32 v5, 1, v3
	v_cmp_ge_f32_e64 s[8:9], 0, v6
	s_nop 1
	v_cndmask_b32_e64 v4, v3, v4, s[8:9]
	v_fma_f32 v3, -v5, v3, v2
	v_cmp_lt_f32_e64 s[8:9], 0, v3
	s_nop 1
	v_cndmask_b32_e64 v3, v4, v5, s[8:9]
	v_mul_f32_e32 v4, 0x37800000, v3
	v_cndmask_b32_e32 v3, v3, v4, vcc
	v_cmp_class_f32_e32 vcc, v2, v226
	s_nop 1
	v_cndmask_b32_e32 v2, v3, v2, vcc
	v_div_scale_f32 v3, s[8:9], v2, v2, 1.0
	v_rcp_f32_e32 v4, v3
	s_nop 0
	v_fma_f32 v5, -v3, v4, 1.0
	v_fmac_f32_e32 v4, v5, v4
	v_div_scale_f32 v5, vcc, 1.0, v2, 1.0
	v_mul_f32_e32 v6, v5, v4
	v_fma_f32 v7, -v3, v6, v5
	v_fmac_f32_e32 v6, v7, v4
	v_fma_f32 v3, -v3, v6, v5
	v_div_fmas_f32 v3, v3, v4, v6
	v_div_fixup_f32 v2, v3, v2, 1.0
	v_lshl_add_u32 v3, v146, 2, s13
	ds_write_b32 v3, v2
	s_or_b64 exec, exec, s[0:1]
	s_and_saveexec_b64 s[0:1], s[6:7]
	s_cbranch_execnz .LBB0_864
